# v11 plus out/down residual epilogue: counted vmcnt(15)/(14) waits per row group instead of one vmcnt(0) after the 16 residual loads
# speedup vs baseline: 1.0012x; 1.0012x over previous
.LBB0_780:
	v_lshl_or_b32 v132, s10, 8, v195
	v_lshl_add_u32 v130, s48, 8, v1
	v_ashrrev_i32_e32 v133, 31, v132
	v_lshlrev_b64 v[220:221], 1, v[132:133]
	v_ashrrev_i32_e32 v131, 31, v130
	v_lshl_add_u64 v[132:133], s[4:5], 0, v[220:221]
	v_lshlrev_b64 v[248:249], 13, v[130:131]
	v_lshl_add_u64 v[134:135], v[132:133], 0, v[248:249]
	global_load_dwordx4 v[244:247], v[134:135], off
	global_load_dwordx4 v[186:189], v[134:135], off offset:256
	v_or_b32_e32 v134, 16, v130
	v_ashrrev_i32_e32 v135, 31, v134
	v_lshlrev_b64 v[234:235], 13, v[134:135]
	v_lshl_add_u64 v[134:135], v[132:133], 0, v[234:235]
	global_load_dwordx4 v[182:185], v[134:135], off
	global_load_dwordx4 v[178:181], v[134:135], off offset:256
	v_or_b32_e32 v134, 32, v130
	v_ashrrev_i32_e32 v135, 31, v134
	v_lshlrev_b64 v[232:233], 13, v[134:135]
	v_lshl_add_u64 v[134:135], v[132:133], 0, v[232:233]
	global_load_dwordx4 v[174:177], v[134:135], off
	global_load_dwordx4 v[166:169], v[134:135], off offset:256
	v_or_b32_e32 v130, 48, v130
	v_ashrrev_i32_e32 v131, 31, v130
	v_lshlrev_b64 v[230:231], 13, v[130:131]
	v_lshl_add_u64 v[130:131], v[132:133], 0, v[230:231]
	global_load_dwordx4 v[170:173], v[130:131], off
	global_load_dwordx4 v[162:165], v[130:131], off offset:256
	s_mov_b64 s[12:13], 0x100000
	v_lshl_add_u64 v[228:229], v[248:249], 0, s[12:13]
	v_lshl_add_u64 v[130:131], v[132:133], 0, v[228:229]
	global_load_dwordx4 v[158:161], v[130:131], off
	global_load_dwordx4 v[154:157], v[130:131], off offset:256
	s_mov_b64 s[12:13], 0x120000
	v_lshl_add_u64 v[226:227], v[248:249], 0, s[12:13]
	v_lshl_add_u64 v[130:131], v[132:133], 0, v[226:227]
	s_mov_b64 s[12:13], 0x140000
	global_load_dwordx4 v[150:153], v[130:131], off
	global_load_dwordx4 v[146:149], v[130:131], off offset:256
	v_lshl_add_u64 v[224:225], v[248:249], 0, s[12:13]
	s_mov_b64 s[12:13], 0x160000
	v_lshl_add_u64 v[130:131], v[132:133], 0, v[224:225]
	v_lshl_add_u64 v[222:223], v[248:249], 0, s[12:13]
	global_load_dwordx4 v[142:145], v[130:131], off
	global_load_dwordx4 v[138:141], v[130:131], off offset:256
	v_lshl_add_u64 v[130:131], v[132:133], 0, v[222:223]
	global_load_dwordx4 v[134:137], v[130:131], off
	s_nop 0
	global_load_dwordx4 v[130:133], v[130:131], off offset:256
	s_mov_b64 s[48:49], -1
	s_andn2_b64 vcc, exec, s[38:39]
	s_waitcnt vmcnt(15)
	v_lshlrev_b32_e32 v243, 16, v244
	v_fmamk_f32 v126, v243, 0x3fb504f3, v126
	v_and_b32_e32 v243, 0xffff0000, v244
	v_fmamk_f32 v127, v243, 0x3fb504f3, v127
	v_cvt_pk_bf16_f32 v126, v126, v127
	v_lshlrev_b32_e32 v127, 16, v245
	v_fmamk_f32 v127, v127, 0x3fb504f3, v128
	v_and_b32_e32 v128, 0xffff0000, v245
	v_fmac_f32_e32 v129, 0x3fb504f3, v128
	v_lshlrev_b32_e32 v128, 16, v246
	v_fmamk_f32 v122, v128, 0x3fb504f3, v122
	v_and_b32_e32 v128, 0xffff0000, v246
	v_cvt_pk_bf16_f32 v127, v127, v129
	v_fmamk_f32 v123, v128, 0x3fb504f3, v123
	v_cvt_pk_bf16_f32 v128, v122, v123
	v_lshlrev_b32_e32 v122, 16, v247
	v_fmamk_f32 v122, v122, 0x3fb504f3, v124
	v_and_b32_e32 v123, 0xffff0000, v247
	s_waitcnt vmcnt(14)
	v_lshlrev_b32_e32 v124, 16, v186
	v_fmac_f32_e32 v125, 0x3fb504f3, v123
	v_cvt_pk_bf16_f32 v129, v122, v125
	v_lshl_add_u64 v[122:123], s[22:23], 0, v[248:249]
	v_fmamk_f32 v118, v124, 0x3fb504f3, v118
	v_and_b32_e32 v124, 0xffff0000, v186
	v_lshl_add_u64 v[122:123], v[122:123], 0, v[220:221]
	v_fmamk_f32 v119, v124, 0x3fb504f3, v119
	global_store_dwordx4 v[122:123], v[126:129], off
	v_cvt_pk_bf16_f32 v118, v118, v119
	v_lshlrev_b32_e32 v119, 16, v187
	v_fmamk_f32 v119, v119, 0x3fb504f3, v120
	v_and_b32_e32 v120, 0xffff0000, v187
	v_fmac_f32_e32 v121, 0x3fb504f3, v120
	v_lshlrev_b32_e32 v120, 16, v188
	v_fmamk_f32 v114, v120, 0x3fb504f3, v114
	v_and_b32_e32 v120, 0xffff0000, v188
	v_cvt_pk_bf16_f32 v119, v119, v121
	v_fmamk_f32 v115, v120, 0x3fb504f3, v115
	v_cvt_pk_bf16_f32 v120, v114, v115
	v_lshlrev_b32_e32 v114, 16, v189
	v_fmamk_f32 v114, v114, 0x3fb504f3, v116
	v_and_b32_e32 v115, 0xffff0000, v189
	v_fmac_f32_e32 v117, 0x3fb504f3, v115
	v_cvt_pk_bf16_f32 v121, v114, v117
	s_waitcnt vmcnt(14)
	v_lshlrev_b32_e32 v114, 16, v182
	v_fmamk_f32 v110, v114, 0x3fb504f3, v110
	v_and_b32_e32 v114, 0xffff0000, v182
	v_fmamk_f32 v111, v114, 0x3fb504f3, v111
	global_store_dwordx4 v[122:123], v[118:121], off offset:256
	v_cvt_pk_bf16_f32 v110, v110, v111
	v_lshlrev_b32_e32 v111, 16, v183
	v_fmamk_f32 v111, v111, 0x3fb504f3, v112
	v_and_b32_e32 v112, 0xffff0000, v183
	v_fmac_f32_e32 v113, 0x3fb504f3, v112
	v_lshlrev_b32_e32 v112, 16, v184
	v_fmamk_f32 v106, v112, 0x3fb504f3, v106
	v_and_b32_e32 v112, 0xffff0000, v184
	v_cvt_pk_bf16_f32 v111, v111, v113
	v_fmamk_f32 v107, v112, 0x3fb504f3, v107
	v_cvt_pk_bf16_f32 v112, v106, v107
	v_lshlrev_b32_e32 v106, 16, v185
	v_fmamk_f32 v106, v106, 0x3fb504f3, v108
	v_and_b32_e32 v107, 0xffff0000, v185
	s_waitcnt vmcnt(14)
	v_lshlrev_b32_e32 v108, 16, v178
	v_fmac_f32_e32 v109, 0x3fb504f3, v107
	v_cvt_pk_bf16_f32 v113, v106, v109
	v_lshl_add_u64 v[106:107], s[22:23], 0, v[234:235]
	v_fmamk_f32 v102, v108, 0x3fb504f3, v102
	v_and_b32_e32 v108, 0xffff0000, v178
	v_lshl_add_u64 v[106:107], v[106:107], 0, v[220:221]
	v_fmamk_f32 v103, v108, 0x3fb504f3, v103
	global_store_dwordx4 v[106:107], v[110:113], off
	v_cvt_pk_bf16_f32 v102, v102, v103
	v_lshlrev_b32_e32 v103, 16, v179
	v_fmamk_f32 v103, v103, 0x3fb504f3, v104
	v_and_b32_e32 v104, 0xffff0000, v179
	v_fmac_f32_e32 v105, 0x3fb504f3, v104
	v_lshlrev_b32_e32 v104, 16, v180
	v_fmamk_f32 v94, v104, 0x3fb504f3, v94
	v_and_b32_e32 v104, 0xffff0000, v180
	v_cvt_pk_bf16_f32 v103, v103, v105
	v_fmamk_f32 v95, v104, 0x3fb504f3, v95
	v_cvt_pk_bf16_f32 v104, v94, v95
	v_lshlrev_b32_e32 v94, 16, v181
	v_fmamk_f32 v94, v94, 0x3fb504f3, v96
	v_and_b32_e32 v95, 0xffff0000, v181
	v_fmac_f32_e32 v97, 0x3fb504f3, v95
	v_cvt_pk_bf16_f32 v105, v94, v97
	s_waitcnt vmcnt(14)
	v_lshlrev_b32_e32 v94, 16, v174
	v_and_b32_e32 v95, 0xffff0000, v174
	v_fmamk_f32 v94, v94, 0x3fb504f3, v98
	v_fmamk_f32 v95, v95, 0x3fb504f3, v99
	v_and_b32_e32 v96, 0xffff0000, v175
	global_store_dwordx4 v[106:107], v[102:105], off offset:256
	v_cvt_pk_bf16_f32 v94, v94, v95
	v_lshlrev_b32_e32 v95, 16, v175
	v_fmac_f32_e32 v101, 0x3fb504f3, v96
	v_lshlrev_b32_e32 v96, 16, v176
	v_fmamk_f32 v95, v95, 0x3fb504f3, v100
	v_fmamk_f32 v90, v96, 0x3fb504f3, v90
	v_and_b32_e32 v96, 0xffff0000, v176
	v_cvt_pk_bf16_f32 v95, v95, v101
	v_fmamk_f32 v91, v96, 0x3fb504f3, v91
	v_cvt_pk_bf16_f32 v96, v90, v91
	v_lshlrev_b32_e32 v90, 16, v177
	v_fmamk_f32 v90, v90, 0x3fb504f3, v92
	v_and_b32_e32 v91, 0xffff0000, v177
	s_waitcnt vmcnt(14)
	v_lshlrev_b32_e32 v92, 16, v166
	v_fmac_f32_e32 v93, 0x3fb504f3, v91
	v_cvt_pk_bf16_f32 v97, v90, v93
	v_lshl_add_u64 v[90:91], s[22:23], 0, v[232:233]
	v_fmamk_f32 v86, v92, 0x3fb504f3, v86
	v_and_b32_e32 v92, 0xffff0000, v166
	v_lshl_add_u64 v[90:91], v[90:91], 0, v[220:221]
	v_fmamk_f32 v87, v92, 0x3fb504f3, v87
	global_store_dwordx4 v[90:91], v[94:97], off
	v_cvt_pk_bf16_f32 v86, v86, v87
	v_lshlrev_b32_e32 v87, 16, v167
	v_fmamk_f32 v87, v87, 0x3fb504f3, v88
	v_and_b32_e32 v88, 0xffff0000, v167
	v_fmac_f32_e32 v89, 0x3fb504f3, v88
	v_lshlrev_b32_e32 v88, 16, v168
	v_fmamk_f32 v78, v88, 0x3fb504f3, v78
	v_and_b32_e32 v88, 0xffff0000, v168
	v_cvt_pk_bf16_f32 v87, v87, v89
	v_fmamk_f32 v79, v88, 0x3fb504f3, v79
	v_cvt_pk_bf16_f32 v88, v78, v79
	v_lshlrev_b32_e32 v78, 16, v169
	v_fmamk_f32 v78, v78, 0x3fb504f3, v80
	v_and_b32_e32 v79, 0xffff0000, v169
	v_fmac_f32_e32 v81, 0x3fb504f3, v79
	v_cvt_pk_bf16_f32 v89, v78, v81
	s_waitcnt vmcnt(14)
	v_lshlrev_b32_e32 v78, 16, v170
	v_and_b32_e32 v79, 0xffff0000, v170
	v_fmamk_f32 v78, v78, 0x3fb504f3, v82
	v_fmamk_f32 v79, v79, 0x3fb504f3, v83
	v_and_b32_e32 v80, 0xffff0000, v171
	global_store_dwordx4 v[90:91], v[86:89], off offset:256
	v_cvt_pk_bf16_f32 v78, v78, v79
	v_lshlrev_b32_e32 v79, 16, v171
	v_fmac_f32_e32 v85, 0x3fb504f3, v80
	v_lshlrev_b32_e32 v80, 16, v172
	v_fmamk_f32 v79, v79, 0x3fb504f3, v84
	v_fmamk_f32 v74, v80, 0x3fb504f3, v74
	v_and_b32_e32 v80, 0xffff0000, v172
	v_cvt_pk_bf16_f32 v79, v79, v85
	v_fmamk_f32 v75, v80, 0x3fb504f3, v75
	v_cvt_pk_bf16_f32 v80, v74, v75
	v_lshlrev_b32_e32 v74, 16, v173
	v_fmamk_f32 v74, v74, 0x3fb504f3, v76
	v_and_b32_e32 v75, 0xffff0000, v173
	s_waitcnt vmcnt(14)
	v_lshlrev_b32_e32 v76, 16, v162
	v_fmac_f32_e32 v77, 0x3fb504f3, v75
	v_cvt_pk_bf16_f32 v81, v74, v77
	v_lshl_add_u64 v[74:75], s[22:23], 0, v[230:231]
	v_fmamk_f32 v70, v76, 0x3fb504f3, v70
	v_and_b32_e32 v76, 0xffff0000, v162
	v_lshl_add_u64 v[74:75], v[74:75], 0, v[220:221]
	v_fmamk_f32 v71, v76, 0x3fb504f3, v71
	global_store_dwordx4 v[74:75], v[78:81], off
	v_cvt_pk_bf16_f32 v70, v70, v71
	v_lshlrev_b32_e32 v71, 16, v163
	v_fmamk_f32 v71, v71, 0x3fb504f3, v72
	v_and_b32_e32 v72, 0xffff0000, v163
	v_fmac_f32_e32 v73, 0x3fb504f3, v72
	v_lshlrev_b32_e32 v72, 16, v164
	v_fmamk_f32 v66, v72, 0x3fb504f3, v66
	v_and_b32_e32 v72, 0xffff0000, v164
	v_cvt_pk_bf16_f32 v71, v71, v73
	v_fmamk_f32 v67, v72, 0x3fb504f3, v67
	v_cvt_pk_bf16_f32 v72, v66, v67
	v_lshlrev_b32_e32 v66, 16, v165
	v_fmamk_f32 v66, v66, 0x3fb504f3, v68
	v_and_b32_e32 v67, 0xffff0000, v165
	v_fmac_f32_e32 v69, 0x3fb504f3, v67
	v_cvt_pk_bf16_f32 v73, v66, v69
	s_waitcnt vmcnt(14)
	v_lshlrev_b32_e32 v66, 16, v158
	v_fmamk_f32 v62, v66, 0x3fb504f3, v62
	v_and_b32_e32 v66, 0xffff0000, v158
	v_fmamk_f32 v63, v66, 0x3fb504f3, v63
	global_store_dwordx4 v[74:75], v[70:73], off offset:256
	v_cvt_pk_bf16_f32 v62, v62, v63
	v_lshlrev_b32_e32 v63, 16, v159
	v_fmamk_f32 v63, v63, 0x3fb504f3, v64
	v_and_b32_e32 v64, 0xffff0000, v159
	v_fmac_f32_e32 v65, 0x3fb504f3, v64
	v_lshlrev_b32_e32 v64, 16, v160
	v_fmamk_f32 v58, v64, 0x3fb504f3, v58
	v_and_b32_e32 v64, 0xffff0000, v160
	v_cvt_pk_bf16_f32 v63, v63, v65
	v_fmamk_f32 v59, v64, 0x3fb504f3, v59
	v_cvt_pk_bf16_f32 v64, v58, v59
	v_lshlrev_b32_e32 v58, 16, v161
	v_fmamk_f32 v58, v58, 0x3fb504f3, v60
	v_and_b32_e32 v59, 0xffff0000, v161
	s_waitcnt vmcnt(14)
	v_lshlrev_b32_e32 v60, 16, v154
	v_fmac_f32_e32 v61, 0x3fb504f3, v59
	v_cvt_pk_bf16_f32 v65, v58, v61
	v_lshl_add_u64 v[58:59], s[22:23], 0, v[228:229]
	v_fmamk_f32 v54, v60, 0x3fb504f3, v54
	v_and_b32_e32 v60, 0xffff0000, v154
	v_lshl_add_u64 v[58:59], v[58:59], 0, v[220:221]
	v_fmamk_f32 v55, v60, 0x3fb504f3, v55
	global_store_dwordx4 v[58:59], v[62:65], off
	v_cvt_pk_bf16_f32 v54, v54, v55
	v_lshlrev_b32_e32 v55, 16, v155
	v_fmamk_f32 v55, v55, 0x3fb504f3, v56
	v_and_b32_e32 v56, 0xffff0000, v155
	v_fmac_f32_e32 v57, 0x3fb504f3, v56
	v_lshlrev_b32_e32 v56, 16, v156
	v_fmamk_f32 v46, v56, 0x3fb504f3, v46
	v_and_b32_e32 v56, 0xffff0000, v156
	v_cvt_pk_bf16_f32 v55, v55, v57
	v_fmamk_f32 v47, v56, 0x3fb504f3, v47
	v_cvt_pk_bf16_f32 v56, v46, v47
	v_lshlrev_b32_e32 v46, 16, v157
	v_fmamk_f32 v46, v46, 0x3fb504f3, v48
	v_and_b32_e32 v47, 0xffff0000, v157
	v_fmac_f32_e32 v49, 0x3fb504f3, v47
	v_cvt_pk_bf16_f32 v57, v46, v49
	s_waitcnt vmcnt(14)
	v_lshlrev_b32_e32 v46, 16, v150
	v_and_b32_e32 v47, 0xffff0000, v150
	v_fmamk_f32 v46, v46, 0x3fb504f3, v50
	v_fmamk_f32 v47, v47, 0x3fb504f3, v51
	v_and_b32_e32 v48, 0xffff0000, v151
	global_store_dwordx4 v[58:59], v[54:57], off offset:256
	v_cvt_pk_bf16_f32 v46, v46, v47
	v_lshlrev_b32_e32 v47, 16, v151
	v_fmac_f32_e32 v53, 0x3fb504f3, v48
	v_lshlrev_b32_e32 v48, 16, v152
	v_fmamk_f32 v47, v47, 0x3fb504f3, v52
	v_fmamk_f32 v42, v48, 0x3fb504f3, v42
	v_and_b32_e32 v48, 0xffff0000, v152
	v_cvt_pk_bf16_f32 v47, v47, v53
	v_fmamk_f32 v43, v48, 0x3fb504f3, v43
	v_cvt_pk_bf16_f32 v48, v42, v43
	v_lshlrev_b32_e32 v42, 16, v153
	v_fmamk_f32 v42, v42, 0x3fb504f3, v44
	v_and_b32_e32 v43, 0xffff0000, v153
	s_waitcnt vmcnt(14)
	v_lshlrev_b32_e32 v44, 16, v146
	v_fmac_f32_e32 v45, 0x3fb504f3, v43
	v_cvt_pk_bf16_f32 v49, v42, v45
	v_lshl_add_u64 v[42:43], s[22:23], 0, v[226:227]
	v_fmamk_f32 v38, v44, 0x3fb504f3, v38
	v_and_b32_e32 v44, 0xffff0000, v146
	v_lshl_add_u64 v[42:43], v[42:43], 0, v[220:221]
	v_fmamk_f32 v39, v44, 0x3fb504f3, v39
	global_store_dwordx4 v[42:43], v[46:49], off
	v_cvt_pk_bf16_f32 v38, v38, v39
	v_lshlrev_b32_e32 v39, 16, v147
	v_fmamk_f32 v39, v39, 0x3fb504f3, v40
	v_and_b32_e32 v40, 0xffff0000, v147
	v_fmac_f32_e32 v41, 0x3fb504f3, v40
	v_lshlrev_b32_e32 v40, 16, v148
	v_fmamk_f32 v30, v40, 0x3fb504f3, v30
	v_and_b32_e32 v40, 0xffff0000, v148
	v_cvt_pk_bf16_f32 v39, v39, v41
	v_fmamk_f32 v31, v40, 0x3fb504f3, v31
	v_cvt_pk_bf16_f32 v40, v30, v31
	v_lshlrev_b32_e32 v30, 16, v149
	v_fmamk_f32 v30, v30, 0x3fb504f3, v32
	v_and_b32_e32 v31, 0xffff0000, v149
	v_fmac_f32_e32 v33, 0x3fb504f3, v31
	v_cvt_pk_bf16_f32 v41, v30, v33
	s_waitcnt vmcnt(14)
	v_lshlrev_b32_e32 v30, 16, v142
	v_and_b32_e32 v31, 0xffff0000, v142
	v_fmamk_f32 v30, v30, 0x3fb504f3, v34
	v_fmamk_f32 v31, v31, 0x3fb504f3, v35
	v_and_b32_e32 v32, 0xffff0000, v143
	global_store_dwordx4 v[42:43], v[38:41], off offset:256
	v_cvt_pk_bf16_f32 v30, v30, v31
	v_lshlrev_b32_e32 v31, 16, v143
	v_fmac_f32_e32 v37, 0x3fb504f3, v32
	v_lshlrev_b32_e32 v32, 16, v144
	v_fmamk_f32 v31, v31, 0x3fb504f3, v36
	v_fmamk_f32 v26, v32, 0x3fb504f3, v26
	v_and_b32_e32 v32, 0xffff0000, v144
	v_cvt_pk_bf16_f32 v31, v31, v37
	v_fmamk_f32 v27, v32, 0x3fb504f3, v27
	v_cvt_pk_bf16_f32 v32, v26, v27
	v_lshlrev_b32_e32 v26, 16, v145
	v_fmamk_f32 v26, v26, 0x3fb504f3, v28
	v_and_b32_e32 v27, 0xffff0000, v145
	s_waitcnt vmcnt(14)
	v_lshlrev_b32_e32 v28, 16, v138
	v_fmac_f32_e32 v29, 0x3fb504f3, v27
	v_cvt_pk_bf16_f32 v33, v26, v29
	v_lshl_add_u64 v[26:27], s[22:23], 0, v[224:225]
	v_fmamk_f32 v22, v28, 0x3fb504f3, v22
	v_and_b32_e32 v28, 0xffff0000, v138
	v_lshl_add_u64 v[26:27], v[26:27], 0, v[220:221]
	v_fmamk_f32 v23, v28, 0x3fb504f3, v23
	global_store_dwordx4 v[26:27], v[30:33], off
	v_cvt_pk_bf16_f32 v22, v22, v23
	v_lshlrev_b32_e32 v23, 16, v139
	v_fmamk_f32 v23, v23, 0x3fb504f3, v24
	v_and_b32_e32 v24, 0xffff0000, v139
	v_fmac_f32_e32 v25, 0x3fb504f3, v24
	v_lshlrev_b32_e32 v24, 16, v140
	v_fmamk_f32 v14, v24, 0x3fb504f3, v14
	v_and_b32_e32 v24, 0xffff0000, v140
	v_cvt_pk_bf16_f32 v23, v23, v25
	v_fmamk_f32 v15, v24, 0x3fb504f3, v15
	v_cvt_pk_bf16_f32 v24, v14, v15
	v_lshlrev_b32_e32 v14, 16, v141
	v_fmamk_f32 v14, v14, 0x3fb504f3, v16
	v_and_b32_e32 v15, 0xffff0000, v141
	v_fmac_f32_e32 v17, 0x3fb504f3, v15
	v_cvt_pk_bf16_f32 v25, v14, v17
	s_waitcnt vmcnt(14)
	v_lshlrev_b32_e32 v14, 16, v134
	v_and_b32_e32 v15, 0xffff0000, v134
	v_fmamk_f32 v14, v14, 0x3fb504f3, v18
	v_fmamk_f32 v15, v15, 0x3fb504f3, v19
	v_and_b32_e32 v16, 0xffff0000, v135
	global_store_dwordx4 v[26:27], v[22:25], off offset:256
	v_cvt_pk_bf16_f32 v14, v14, v15
	v_lshlrev_b32_e32 v15, 16, v135
	v_fmac_f32_e32 v21, 0x3fb504f3, v16
	v_lshlrev_b32_e32 v16, 16, v136
	v_fmamk_f32 v15, v15, 0x3fb504f3, v20
	v_fmamk_f32 v10, v16, 0x3fb504f3, v10
	v_and_b32_e32 v16, 0xffff0000, v136
	v_cvt_pk_bf16_f32 v15, v15, v21
	v_fmamk_f32 v11, v16, 0x3fb504f3, v11
	v_cvt_pk_bf16_f32 v16, v10, v11
	v_lshlrev_b32_e32 v10, 16, v137
	v_fmamk_f32 v10, v10, 0x3fb504f3, v12
	v_and_b32_e32 v11, 0xffff0000, v137
	s_waitcnt vmcnt(14)
	v_lshlrev_b32_e32 v12, 16, v130
	v_fmac_f32_e32 v13, 0x3fb504f3, v11
	v_cvt_pk_bf16_f32 v17, v10, v13
	v_lshl_add_u64 v[10:11], s[22:23], 0, v[222:223]
	v_fmamk_f32 v6, v12, 0x3fb504f3, v6
	v_and_b32_e32 v12, 0xffff0000, v130
	v_lshl_add_u64 v[10:11], v[10:11], 0, v[220:221]
	v_fmamk_f32 v7, v12, 0x3fb504f3, v7
	global_store_dwordx4 v[10:11], v[14:17], off
	v_cvt_pk_bf16_f32 v6, v6, v7
	v_lshlrev_b32_e32 v7, 16, v131
	v_fmamk_f32 v7, v7, 0x3fb504f3, v8
	v_and_b32_e32 v8, 0xffff0000, v131
	v_fmac_f32_e32 v9, 0x3fb504f3, v8
	v_lshlrev_b32_e32 v8, 16, v132
	v_fmamk_f32 v2, v8, 0x3fb504f3, v2
	v_and_b32_e32 v8, 0xffff0000, v132
	v_fmamk_f32 v3, v8, 0x3fb504f3, v3
	v_cvt_pk_bf16_f32 v7, v7, v9
	v_cvt_pk_bf16_f32 v8, v2, v3
	v_lshlrev_b32_e32 v2, 16, v133
	v_and_b32_e32 v3, 0xffff0000, v133
	v_fmamk_f32 v2, v2, 0x3fb504f3, v4
	v_fmac_f32_e32 v5, 0x3fb504f3, v3
	v_cvt_pk_bf16_f32 v9, v2, v5
	global_store_dwordx4 v[10:11], v[6:9], off offset:256
	s_cbranch_vccnz .LBB0_769
	s_andn2_b64 vcc, exec, s[0:1]
	s_cbranch_vccnz .LBB0_768
	s_barrier
	s_branch .LBB0_768

.LBB0_986:
	v_lshl_or_b32 v132, s10, 8, v195
	v_lshl_add_u32 v130, s68, 8, v1
	v_ashrrev_i32_e32 v133, 31, v132
	v_lshlrev_b64 v[220:221], 1, v[132:133]
	v_ashrrev_i32_e32 v131, 31, v130
	v_lshl_add_u64 v[132:133], s[22:23], 0, v[220:221]
	v_lshlrev_b64 v[248:249], 13, v[130:131]
	v_lshl_add_u64 v[134:135], v[132:133], 0, v[248:249]
	global_load_dwordx4 v[244:247], v[134:135], off
	global_load_dwordx4 v[186:189], v[134:135], off offset:256
	v_or_b32_e32 v134, 16, v130
	v_ashrrev_i32_e32 v135, 31, v134
	v_lshlrev_b64 v[234:235], 13, v[134:135]
	v_lshl_add_u64 v[134:135], v[132:133], 0, v[234:235]
	global_load_dwordx4 v[182:185], v[134:135], off
	global_load_dwordx4 v[178:181], v[134:135], off offset:256
	v_or_b32_e32 v134, 32, v130
	v_ashrrev_i32_e32 v135, 31, v134
	v_lshlrev_b64 v[232:233], 13, v[134:135]
	v_lshl_add_u64 v[134:135], v[132:133], 0, v[232:233]
	global_load_dwordx4 v[174:177], v[134:135], off
	global_load_dwordx4 v[166:169], v[134:135], off offset:256
	v_or_b32_e32 v130, 48, v130
	v_ashrrev_i32_e32 v131, 31, v130
	v_lshlrev_b64 v[230:231], 13, v[130:131]
	v_lshl_add_u64 v[130:131], v[132:133], 0, v[230:231]
	global_load_dwordx4 v[170:173], v[130:131], off
	global_load_dwordx4 v[162:165], v[130:131], off offset:256
	s_mov_b64 s[12:13], 0x100000
	v_lshl_add_u64 v[228:229], v[248:249], 0, s[12:13]
	v_lshl_add_u64 v[130:131], v[132:133], 0, v[228:229]
	global_load_dwordx4 v[158:161], v[130:131], off
	global_load_dwordx4 v[154:157], v[130:131], off offset:256
	s_mov_b64 s[12:13], 0x120000
	v_lshl_add_u64 v[226:227], v[248:249], 0, s[12:13]
	v_lshl_add_u64 v[130:131], v[132:133], 0, v[226:227]
	s_mov_b64 s[12:13], 0x140000
	global_load_dwordx4 v[150:153], v[130:131], off
	global_load_dwordx4 v[146:149], v[130:131], off offset:256
	v_lshl_add_u64 v[224:225], v[248:249], 0, s[12:13]
	s_mov_b64 s[12:13], 0x160000
	v_lshl_add_u64 v[130:131], v[132:133], 0, v[224:225]
	v_lshl_add_u64 v[222:223], v[248:249], 0, s[12:13]
	global_load_dwordx4 v[142:145], v[130:131], off
	global_load_dwordx4 v[138:141], v[130:131], off offset:256
	v_lshl_add_u64 v[130:131], v[132:133], 0, v[222:223]
	global_load_dwordx4 v[134:137], v[130:131], off
	s_nop 0
	global_load_dwordx4 v[130:133], v[130:131], off offset:256
	s_mov_b64 s[44:45], -1
	s_and_b64 vcc, exec, s[38:39]
	s_waitcnt vmcnt(15)
	v_lshlrev_b32_e32 v243, 16, v244
	v_fmamk_f32 v126, v243, 0x3fb504f3, v126
	v_and_b32_e32 v243, 0xffff0000, v244
	v_fmamk_f32 v127, v243, 0x3fb504f3, v127
	v_cvt_pk_bf16_f32 v126, v126, v127
	v_lshlrev_b32_e32 v127, 16, v245
	v_fmamk_f32 v127, v127, 0x3fb504f3, v128
	v_and_b32_e32 v128, 0xffff0000, v245
	v_fmac_f32_e32 v129, 0x3fb504f3, v128
	v_lshlrev_b32_e32 v128, 16, v246
	v_fmamk_f32 v122, v128, 0x3fb504f3, v122
	v_and_b32_e32 v128, 0xffff0000, v246
	v_cvt_pk_bf16_f32 v127, v127, v129
	v_fmamk_f32 v123, v128, 0x3fb504f3, v123
	v_cvt_pk_bf16_f32 v128, v122, v123
	v_lshlrev_b32_e32 v122, 16, v247
	v_fmamk_f32 v122, v122, 0x3fb504f3, v124
	v_and_b32_e32 v123, 0xffff0000, v247
	s_waitcnt vmcnt(14)
	v_lshlrev_b32_e32 v124, 16, v186
	v_fmac_f32_e32 v125, 0x3fb504f3, v123
	v_cvt_pk_bf16_f32 v129, v122, v125
	v_lshl_add_u64 v[122:123], s[4:5], 0, v[248:249]
	v_fmamk_f32 v118, v124, 0x3fb504f3, v118
	v_and_b32_e32 v124, 0xffff0000, v186
	v_lshl_add_u64 v[122:123], v[122:123], 0, v[220:221]
	v_fmamk_f32 v119, v124, 0x3fb504f3, v119
	global_store_dwordx4 v[122:123], v[126:129], off
	v_cvt_pk_bf16_f32 v118, v118, v119
	v_lshlrev_b32_e32 v119, 16, v187
	v_fmamk_f32 v119, v119, 0x3fb504f3, v120
	v_and_b32_e32 v120, 0xffff0000, v187
	v_fmac_f32_e32 v121, 0x3fb504f3, v120
	v_lshlrev_b32_e32 v120, 16, v188
	v_fmamk_f32 v114, v120, 0x3fb504f3, v114
	v_and_b32_e32 v120, 0xffff0000, v188
	v_cvt_pk_bf16_f32 v119, v119, v121
	v_fmamk_f32 v115, v120, 0x3fb504f3, v115
	v_cvt_pk_bf16_f32 v120, v114, v115
	v_lshlrev_b32_e32 v114, 16, v189
	v_fmamk_f32 v114, v114, 0x3fb504f3, v116
	v_and_b32_e32 v115, 0xffff0000, v189
	v_fmac_f32_e32 v117, 0x3fb504f3, v115
	v_cvt_pk_bf16_f32 v121, v114, v117
	s_waitcnt vmcnt(14)
	v_lshlrev_b32_e32 v114, 16, v182
	v_fmamk_f32 v110, v114, 0x3fb504f3, v110
	v_and_b32_e32 v114, 0xffff0000, v182
	v_fmamk_f32 v111, v114, 0x3fb504f3, v111
	global_store_dwordx4 v[122:123], v[118:121], off offset:256
	v_cvt_pk_bf16_f32 v110, v110, v111
	v_lshlrev_b32_e32 v111, 16, v183
	v_fmamk_f32 v111, v111, 0x3fb504f3, v112
	v_and_b32_e32 v112, 0xffff0000, v183
	v_fmac_f32_e32 v113, 0x3fb504f3, v112
	v_lshlrev_b32_e32 v112, 16, v184
	v_fmamk_f32 v106, v112, 0x3fb504f3, v106
	v_and_b32_e32 v112, 0xffff0000, v184
	v_cvt_pk_bf16_f32 v111, v111, v113
	v_fmamk_f32 v107, v112, 0x3fb504f3, v107
	v_cvt_pk_bf16_f32 v112, v106, v107
	v_lshlrev_b32_e32 v106, 16, v185
	v_fmamk_f32 v106, v106, 0x3fb504f3, v108
	v_and_b32_e32 v107, 0xffff0000, v185
	s_waitcnt vmcnt(14)
	v_lshlrev_b32_e32 v108, 16, v178
	v_fmac_f32_e32 v109, 0x3fb504f3, v107
	v_cvt_pk_bf16_f32 v113, v106, v109
	v_lshl_add_u64 v[106:107], s[4:5], 0, v[234:235]
	v_fmamk_f32 v102, v108, 0x3fb504f3, v102
	v_and_b32_e32 v108, 0xffff0000, v178
	v_lshl_add_u64 v[106:107], v[106:107], 0, v[220:221]
	v_fmamk_f32 v103, v108, 0x3fb504f3, v103
	global_store_dwordx4 v[106:107], v[110:113], off
	v_cvt_pk_bf16_f32 v102, v102, v103
	v_lshlrev_b32_e32 v103, 16, v179
	v_fmamk_f32 v103, v103, 0x3fb504f3, v104
	v_and_b32_e32 v104, 0xffff0000, v179
	v_fmac_f32_e32 v105, 0x3fb504f3, v104
	v_lshlrev_b32_e32 v104, 16, v180
	v_fmamk_f32 v94, v104, 0x3fb504f3, v94
	v_and_b32_e32 v104, 0xffff0000, v180
	v_cvt_pk_bf16_f32 v103, v103, v105
	v_fmamk_f32 v95, v104, 0x3fb504f3, v95
	v_cvt_pk_bf16_f32 v104, v94, v95
	v_lshlrev_b32_e32 v94, 16, v181
	v_fmamk_f32 v94, v94, 0x3fb504f3, v96
	v_and_b32_e32 v95, 0xffff0000, v181
	v_fmac_f32_e32 v97, 0x3fb504f3, v95
	v_cvt_pk_bf16_f32 v105, v94, v97
	s_waitcnt vmcnt(14)
	v_lshlrev_b32_e32 v94, 16, v174
	v_and_b32_e32 v95, 0xffff0000, v174
	v_fmamk_f32 v94, v94, 0x3fb504f3, v98
	v_fmamk_f32 v95, v95, 0x3fb504f3, v99
	v_and_b32_e32 v96, 0xffff0000, v175
	global_store_dwordx4 v[106:107], v[102:105], off offset:256
	v_cvt_pk_bf16_f32 v94, v94, v95
	v_lshlrev_b32_e32 v95, 16, v175
	v_fmac_f32_e32 v101, 0x3fb504f3, v96
	v_lshlrev_b32_e32 v96, 16, v176
	v_fmamk_f32 v95, v95, 0x3fb504f3, v100
	v_fmamk_f32 v90, v96, 0x3fb504f3, v90
	v_and_b32_e32 v96, 0xffff0000, v176
	v_cvt_pk_bf16_f32 v95, v95, v101
	v_fmamk_f32 v91, v96, 0x3fb504f3, v91
	v_cvt_pk_bf16_f32 v96, v90, v91
	v_lshlrev_b32_e32 v90, 16, v177
	v_fmamk_f32 v90, v90, 0x3fb504f3, v92
	v_and_b32_e32 v91, 0xffff0000, v177
	s_waitcnt vmcnt(14)
	v_lshlrev_b32_e32 v92, 16, v166
	v_fmac_f32_e32 v93, 0x3fb504f3, v91
	v_cvt_pk_bf16_f32 v97, v90, v93
	v_lshl_add_u64 v[90:91], s[4:5], 0, v[232:233]
	v_fmamk_f32 v86, v92, 0x3fb504f3, v86
	v_and_b32_e32 v92, 0xffff0000, v166
	v_lshl_add_u64 v[90:91], v[90:91], 0, v[220:221]
	v_fmamk_f32 v87, v92, 0x3fb504f3, v87
	global_store_dwordx4 v[90:91], v[94:97], off
	v_cvt_pk_bf16_f32 v86, v86, v87
	v_lshlrev_b32_e32 v87, 16, v167
	v_fmamk_f32 v87, v87, 0x3fb504f3, v88
	v_and_b32_e32 v88, 0xffff0000, v167
	v_fmac_f32_e32 v89, 0x3fb504f3, v88
	v_lshlrev_b32_e32 v88, 16, v168
	v_fmamk_f32 v78, v88, 0x3fb504f3, v78
	v_and_b32_e32 v88, 0xffff0000, v168
	v_cvt_pk_bf16_f32 v87, v87, v89
	v_fmamk_f32 v79, v88, 0x3fb504f3, v79
	v_cvt_pk_bf16_f32 v88, v78, v79
	v_lshlrev_b32_e32 v78, 16, v169
	v_fmamk_f32 v78, v78, 0x3fb504f3, v80
	v_and_b32_e32 v79, 0xffff0000, v169
	v_fmac_f32_e32 v81, 0x3fb504f3, v79
	v_cvt_pk_bf16_f32 v89, v78, v81
	s_waitcnt vmcnt(14)
	v_lshlrev_b32_e32 v78, 16, v170
	v_and_b32_e32 v79, 0xffff0000, v170
	v_fmamk_f32 v78, v78, 0x3fb504f3, v82
	v_fmamk_f32 v79, v79, 0x3fb504f3, v83
	v_and_b32_e32 v80, 0xffff0000, v171
	global_store_dwordx4 v[90:91], v[86:89], off offset:256
	v_cvt_pk_bf16_f32 v78, v78, v79
	v_lshlrev_b32_e32 v79, 16, v171
	v_fmac_f32_e32 v85, 0x3fb504f3, v80
	v_lshlrev_b32_e32 v80, 16, v172
	v_fmamk_f32 v79, v79, 0x3fb504f3, v84
	v_fmamk_f32 v74, v80, 0x3fb504f3, v74
	v_and_b32_e32 v80, 0xffff0000, v172
	v_cvt_pk_bf16_f32 v79, v79, v85
	v_fmamk_f32 v75, v80, 0x3fb504f3, v75
	v_cvt_pk_bf16_f32 v80, v74, v75
	v_lshlrev_b32_e32 v74, 16, v173
	v_fmamk_f32 v74, v74, 0x3fb504f3, v76
	v_and_b32_e32 v75, 0xffff0000, v173
	s_waitcnt vmcnt(14)
	v_lshlrev_b32_e32 v76, 16, v162
	v_fmac_f32_e32 v77, 0x3fb504f3, v75
	v_cvt_pk_bf16_f32 v81, v74, v77
	v_lshl_add_u64 v[74:75], s[4:5], 0, v[230:231]
	v_fmamk_f32 v70, v76, 0x3fb504f3, v70
	v_and_b32_e32 v76, 0xffff0000, v162
	v_lshl_add_u64 v[74:75], v[74:75], 0, v[220:221]
	v_fmamk_f32 v71, v76, 0x3fb504f3, v71
	global_store_dwordx4 v[74:75], v[78:81], off
	v_cvt_pk_bf16_f32 v70, v70, v71
	v_lshlrev_b32_e32 v71, 16, v163
	v_fmamk_f32 v71, v71, 0x3fb504f3, v72
	v_and_b32_e32 v72, 0xffff0000, v163
	v_fmac_f32_e32 v73, 0x3fb504f3, v72
	v_lshlrev_b32_e32 v72, 16, v164
	v_fmamk_f32 v66, v72, 0x3fb504f3, v66
	v_and_b32_e32 v72, 0xffff0000, v164
	v_cvt_pk_bf16_f32 v71, v71, v73
	v_fmamk_f32 v67, v72, 0x3fb504f3, v67
	v_cvt_pk_bf16_f32 v72, v66, v67
	v_lshlrev_b32_e32 v66, 16, v165
	v_fmamk_f32 v66, v66, 0x3fb504f3, v68
	v_and_b32_e32 v67, 0xffff0000, v165
	v_fmac_f32_e32 v69, 0x3fb504f3, v67
	v_cvt_pk_bf16_f32 v73, v66, v69
	s_waitcnt vmcnt(14)
	v_lshlrev_b32_e32 v66, 16, v158
	v_fmamk_f32 v62, v66, 0x3fb504f3, v62
	v_and_b32_e32 v66, 0xffff0000, v158
	v_fmamk_f32 v63, v66, 0x3fb504f3, v63
	global_store_dwordx4 v[74:75], v[70:73], off offset:256
	v_cvt_pk_bf16_f32 v62, v62, v63
	v_lshlrev_b32_e32 v63, 16, v159
	v_fmamk_f32 v63, v63, 0x3fb504f3, v64
	v_and_b32_e32 v64, 0xffff0000, v159
	v_fmac_f32_e32 v65, 0x3fb504f3, v64
	v_lshlrev_b32_e32 v64, 16, v160
	v_fmamk_f32 v58, v64, 0x3fb504f3, v58
	v_and_b32_e32 v64, 0xffff0000, v160
	v_cvt_pk_bf16_f32 v63, v63, v65
	v_fmamk_f32 v59, v64, 0x3fb504f3, v59
	v_cvt_pk_bf16_f32 v64, v58, v59
	v_lshlrev_b32_e32 v58, 16, v161
	v_fmamk_f32 v58, v58, 0x3fb504f3, v60
	v_and_b32_e32 v59, 0xffff0000, v161
	s_waitcnt vmcnt(14)
	v_lshlrev_b32_e32 v60, 16, v154
	v_fmac_f32_e32 v61, 0x3fb504f3, v59
	v_cvt_pk_bf16_f32 v65, v58, v61
	v_lshl_add_u64 v[58:59], s[4:5], 0, v[228:229]
	v_fmamk_f32 v54, v60, 0x3fb504f3, v54
	v_and_b32_e32 v60, 0xffff0000, v154
	v_lshl_add_u64 v[58:59], v[58:59], 0, v[220:221]
	v_fmamk_f32 v55, v60, 0x3fb504f3, v55
	global_store_dwordx4 v[58:59], v[62:65], off
	v_cvt_pk_bf16_f32 v54, v54, v55
	v_lshlrev_b32_e32 v55, 16, v155
	v_fmamk_f32 v55, v55, 0x3fb504f3, v56
	v_and_b32_e32 v56, 0xffff0000, v155
	v_fmac_f32_e32 v57, 0x3fb504f3, v56
	v_lshlrev_b32_e32 v56, 16, v156
	v_fmamk_f32 v46, v56, 0x3fb504f3, v46
	v_and_b32_e32 v56, 0xffff0000, v156
	v_cvt_pk_bf16_f32 v55, v55, v57
	v_fmamk_f32 v47, v56, 0x3fb504f3, v47
	v_cvt_pk_bf16_f32 v56, v46, v47
	v_lshlrev_b32_e32 v46, 16, v157
	v_fmamk_f32 v46, v46, 0x3fb504f3, v48
	v_and_b32_e32 v47, 0xffff0000, v157
	v_fmac_f32_e32 v49, 0x3fb504f3, v47
	v_cvt_pk_bf16_f32 v57, v46, v49
	s_waitcnt vmcnt(14)
	v_lshlrev_b32_e32 v46, 16, v150
	v_and_b32_e32 v47, 0xffff0000, v150
	v_fmamk_f32 v46, v46, 0x3fb504f3, v50
	v_fmamk_f32 v47, v47, 0x3fb504f3, v51
	v_and_b32_e32 v48, 0xffff0000, v151
	global_store_dwordx4 v[58:59], v[54:57], off offset:256
	v_cvt_pk_bf16_f32 v46, v46, v47
	v_lshlrev_b32_e32 v47, 16, v151
	v_fmac_f32_e32 v53, 0x3fb504f3, v48
	v_lshlrev_b32_e32 v48, 16, v152
	v_fmamk_f32 v47, v47, 0x3fb504f3, v52
	v_fmamk_f32 v42, v48, 0x3fb504f3, v42
	v_and_b32_e32 v48, 0xffff0000, v152
	v_cvt_pk_bf16_f32 v47, v47, v53
	v_fmamk_f32 v43, v48, 0x3fb504f3, v43
	v_cvt_pk_bf16_f32 v48, v42, v43
	v_lshlrev_b32_e32 v42, 16, v153
	v_fmamk_f32 v42, v42, 0x3fb504f3, v44
	v_and_b32_e32 v43, 0xffff0000, v153
	s_waitcnt vmcnt(14)
	v_lshlrev_b32_e32 v44, 16, v146
	v_fmac_f32_e32 v45, 0x3fb504f3, v43
	v_cvt_pk_bf16_f32 v49, v42, v45
	v_lshl_add_u64 v[42:43], s[4:5], 0, v[226:227]
	v_fmamk_f32 v38, v44, 0x3fb504f3, v38
	v_and_b32_e32 v44, 0xffff0000, v146
	v_lshl_add_u64 v[42:43], v[42:43], 0, v[220:221]
	v_fmamk_f32 v39, v44, 0x3fb504f3, v39
	global_store_dwordx4 v[42:43], v[46:49], off
	v_cvt_pk_bf16_f32 v38, v38, v39
	v_lshlrev_b32_e32 v39, 16, v147
	v_fmamk_f32 v39, v39, 0x3fb504f3, v40
	v_and_b32_e32 v40, 0xffff0000, v147
	v_fmac_f32_e32 v41, 0x3fb504f3, v40
	v_lshlrev_b32_e32 v40, 16, v148
	v_fmamk_f32 v30, v40, 0x3fb504f3, v30
	v_and_b32_e32 v40, 0xffff0000, v148
	v_cvt_pk_bf16_f32 v39, v39, v41
	v_fmamk_f32 v31, v40, 0x3fb504f3, v31
	v_cvt_pk_bf16_f32 v40, v30, v31
	v_lshlrev_b32_e32 v30, 16, v149
	v_fmamk_f32 v30, v30, 0x3fb504f3, v32
	v_and_b32_e32 v31, 0xffff0000, v149
	v_fmac_f32_e32 v33, 0x3fb504f3, v31
	v_cvt_pk_bf16_f32 v41, v30, v33
	s_waitcnt vmcnt(14)
	v_lshlrev_b32_e32 v30, 16, v142
	v_and_b32_e32 v31, 0xffff0000, v142
	v_fmamk_f32 v30, v30, 0x3fb504f3, v34
	v_fmamk_f32 v31, v31, 0x3fb504f3, v35
	v_and_b32_e32 v32, 0xffff0000, v143
	global_store_dwordx4 v[42:43], v[38:41], off offset:256
	v_cvt_pk_bf16_f32 v30, v30, v31
	v_lshlrev_b32_e32 v31, 16, v143
	v_fmac_f32_e32 v37, 0x3fb504f3, v32
	v_lshlrev_b32_e32 v32, 16, v144
	v_fmamk_f32 v31, v31, 0x3fb504f3, v36
	v_fmamk_f32 v26, v32, 0x3fb504f3, v26
	v_and_b32_e32 v32, 0xffff0000, v144
	v_cvt_pk_bf16_f32 v31, v31, v37
	v_fmamk_f32 v27, v32, 0x3fb504f3, v27
	v_cvt_pk_bf16_f32 v32, v26, v27
	v_lshlrev_b32_e32 v26, 16, v145
	v_fmamk_f32 v26, v26, 0x3fb504f3, v28
	v_and_b32_e32 v27, 0xffff0000, v145
	s_waitcnt vmcnt(14)
	v_lshlrev_b32_e32 v28, 16, v138
	v_fmac_f32_e32 v29, 0x3fb504f3, v27
	v_cvt_pk_bf16_f32 v33, v26, v29
	v_lshl_add_u64 v[26:27], s[4:5], 0, v[224:225]
	v_fmamk_f32 v22, v28, 0x3fb504f3, v22
	v_and_b32_e32 v28, 0xffff0000, v138
	v_lshl_add_u64 v[26:27], v[26:27], 0, v[220:221]
	v_fmamk_f32 v23, v28, 0x3fb504f3, v23
	global_store_dwordx4 v[26:27], v[30:33], off
	v_cvt_pk_bf16_f32 v22, v22, v23
	v_lshlrev_b32_e32 v23, 16, v139
	v_fmamk_f32 v23, v23, 0x3fb504f3, v24
	v_and_b32_e32 v24, 0xffff0000, v139
	v_fmac_f32_e32 v25, 0x3fb504f3, v24
	v_lshlrev_b32_e32 v24, 16, v140
	v_fmamk_f32 v14, v24, 0x3fb504f3, v14
	v_and_b32_e32 v24, 0xffff0000, v140
	v_cvt_pk_bf16_f32 v23, v23, v25
	v_fmamk_f32 v15, v24, 0x3fb504f3, v15
	v_cvt_pk_bf16_f32 v24, v14, v15
	v_lshlrev_b32_e32 v14, 16, v141
	v_fmamk_f32 v14, v14, 0x3fb504f3, v16
	v_and_b32_e32 v15, 0xffff0000, v141
	v_fmac_f32_e32 v17, 0x3fb504f3, v15
	v_cvt_pk_bf16_f32 v25, v14, v17
	s_waitcnt vmcnt(14)
	v_lshlrev_b32_e32 v14, 16, v134
	v_and_b32_e32 v15, 0xffff0000, v134
	v_fmamk_f32 v14, v14, 0x3fb504f3, v18
	v_fmamk_f32 v15, v15, 0x3fb504f3, v19
	v_and_b32_e32 v16, 0xffff0000, v135
	global_store_dwordx4 v[26:27], v[22:25], off offset:256
	v_cvt_pk_bf16_f32 v14, v14, v15
	v_lshlrev_b32_e32 v15, 16, v135
	v_fmac_f32_e32 v21, 0x3fb504f3, v16
	v_lshlrev_b32_e32 v16, 16, v136
	v_fmamk_f32 v15, v15, 0x3fb504f3, v20
	v_fmamk_f32 v10, v16, 0x3fb504f3, v10
	v_and_b32_e32 v16, 0xffff0000, v136
	v_cvt_pk_bf16_f32 v15, v15, v21
	v_fmamk_f32 v11, v16, 0x3fb504f3, v11
	v_cvt_pk_bf16_f32 v16, v10, v11
	v_lshlrev_b32_e32 v10, 16, v137
	v_fmamk_f32 v10, v10, 0x3fb504f3, v12
	v_and_b32_e32 v11, 0xffff0000, v137
	s_waitcnt vmcnt(14)
	v_lshlrev_b32_e32 v12, 16, v130
	v_fmac_f32_e32 v13, 0x3fb504f3, v11
	v_cvt_pk_bf16_f32 v17, v10, v13
	v_lshl_add_u64 v[10:11], s[4:5], 0, v[222:223]
	v_fmamk_f32 v6, v12, 0x3fb504f3, v6
	v_and_b32_e32 v12, 0xffff0000, v130
	v_lshl_add_u64 v[10:11], v[10:11], 0, v[220:221]
	v_fmamk_f32 v7, v12, 0x3fb504f3, v7
	global_store_dwordx4 v[10:11], v[14:17], off
	v_cvt_pk_bf16_f32 v6, v6, v7
	v_lshlrev_b32_e32 v7, 16, v131
	v_fmamk_f32 v7, v7, 0x3fb504f3, v8
	v_and_b32_e32 v8, 0xffff0000, v131
	v_fmac_f32_e32 v9, 0x3fb504f3, v8
	v_lshlrev_b32_e32 v8, 16, v132
	v_fmamk_f32 v2, v8, 0x3fb504f3, v2
	v_and_b32_e32 v8, 0xffff0000, v132
	v_fmamk_f32 v3, v8, 0x3fb504f3, v3
	v_cvt_pk_bf16_f32 v7, v7, v9
	v_cvt_pk_bf16_f32 v8, v2, v3
	v_lshlrev_b32_e32 v2, 16, v133
	v_and_b32_e32 v3, 0xffff0000, v133
	v_fmamk_f32 v2, v2, 0x3fb504f3, v4
	v_fmac_f32_e32 v5, 0x3fb504f3, v3
	v_cvt_pk_bf16_f32 v9, v2, v5
	global_store_dwordx4 v[10:11], v[6:9], off offset:256
	s_cbranch_vccnz .LBB0_971
	s_andn2_b64 vcc, exec, s[0:1]
	s_cbranch_vccnz .LBB0_970
	s_barrier
	s_branch .LBB0_970
